# write-through also for the last row group's stores of the mixer / FFN-down residual epilogues (no wait follows them in the epilogue); on top of v57
# speedup vs baseline: 1.0028x; 1.0028x over previous
.Lxr2_3:
.LBB0_1073:
	v_mul_f32_e32 v88, v192, v192
	v_mul_f32_e32 v89, v190, v190
	v_fmac_f32_e32 v88, v193, v193
	v_fmac_f32_e32 v89, v191, v191
	v_add_f32_e32 v88, v89, v88
	v_mul_f32_e32 v89, v174, v174
	v_mul_f32_e32 v96, v177, v177
	v_fmac_f32_e32 v89, v175, v175
	v_fmac_f32_e32 v96, v176, v176
	v_add_f32_e32 v89, v96, v89
	v_add_f32_e32 v88, v89, v88
	v_mul_f32_e32 v89, v198, v198
	v_mul_f32_e32 v96, v194, v194
	v_fmac_f32_e32 v89, v199, v199
	v_fmac_f32_e32 v96, v195, v195
	v_add_f32_e32 v89, v96, v89
	v_mul_f32_e32 v96, v110, v110
	v_mul_f32_e32 v97, v113, v113
	v_fmac_f32_e32 v96, v111, v111
	v_fmac_f32_e32 v97, v112, v112
	v_add_f32_e32 v96, v97, v96
	v_add_f32_e32 v89, v96, v89
	v_add_f32_e32 v96, v88, v89
	v_lshl_add_u64 v[88:89], v[226:227], 0, v[120:121]
	s_waitcnt vmcnt(0)
	v_pk_fma_f32 v[26:27], v[26:27], v[74:75], v[62:63]
	v_lshlrev_b64 v[62:63], 1, v[88:89]
	v_pk_fma_f32 v[32:33], v[32:33], v[80:81], v[60:61]
	v_pk_fma_f32 v[30:31], v[30:31], v[78:79], v[58:59]
	v_pk_fma_f32 v[28:29], v[28:29], v[76:77], v[64:65]
	v_cvt_pk_bf16_f32 v58, v30, v31
	v_cvt_pk_bf16_f32 v59, v32, v33
	v_lshl_add_u64 v[64:65], s[12:13], 0, v[62:63]
	v_cvt_pk_bf16_f32 v60, v26, v27
	v_cvt_pk_bf16_f32 v61, v28, v29
	v_lshl_add_u64 v[62:63], s[18:19], 0, v[62:63]
	v_pk_mul_f32 v[64:65], v[68:69], v[28:29]
	v_pk_mul_f32 v[58:59], v[70:71], v[30:31]
	v_pk_mul_f32 v[60:61], v[72:73], v[32:33]
	v_cvt_pk_bf16_f32 v58, v58, v59
	v_pk_mul_f32 v[88:89], v[66:67], v[26:27]
	v_cvt_pk_bf16_f32 v59, v60, v61
	v_pk_fma_f32 v[18:19], v[18:19], v[74:75], v[54:55]
	v_cvt_pk_bf16_f32 v60, v88, v89
	v_cvt_pk_bf16_f32 v61, v64, v65
	flat_store_dwordx4 v[62:63], v[58:61] sc1
	v_pk_fma_f32 v[24:25], v[24:25], v[80:81], v[52:53]
	v_pk_fma_f32 v[22:23], v[22:23], v[78:79], v[50:51]
	v_lshl_add_u64 v[58:59], v[228:229], 0, v[120:121]
	v_lshlrev_b64 v[54:55], 1, v[58:59]
	v_pk_fma_f32 v[20:21], v[20:21], v[76:77], v[56:57]
	v_cvt_pk_bf16_f32 v50, v22, v23
	v_cvt_pk_bf16_f32 v51, v24, v25
	v_lshl_add_u64 v[56:57], s[12:13], 0, v[54:55]
	v_cvt_pk_bf16_f32 v52, v18, v19
	v_cvt_pk_bf16_f32 v53, v20, v21
	v_lshl_add_u64 v[54:55], s[18:19], 0, v[54:55]
	v_pk_mul_f32 v[56:57], v[68:69], v[20:21]
	v_pk_mul_f32 v[50:51], v[70:71], v[22:23]
	v_pk_mul_f32 v[52:53], v[72:73], v[24:25]
	v_cvt_pk_bf16_f32 v50, v50, v51
	v_pk_mul_f32 v[58:59], v[66:67], v[18:19]
	v_cvt_pk_bf16_f32 v51, v52, v53
	v_pk_fma_f32 v[10:11], v[10:11], v[74:75], v[46:47]
	v_cvt_pk_bf16_f32 v52, v58, v59
	v_cvt_pk_bf16_f32 v53, v56, v57
	flat_store_dwordx4 v[54:55], v[50:53] sc1
	v_pk_fma_f32 v[16:17], v[16:17], v[80:81], v[44:45]
	v_pk_fma_f32 v[14:15], v[14:15], v[78:79], v[42:43]
	v_lshl_add_u64 v[50:51], v[230:231], 0, v[120:121]
	v_lshlrev_b64 v[46:47], 1, v[50:51]
	v_pk_fma_f32 v[12:13], v[12:13], v[76:77], v[48:49]
	v_cvt_pk_bf16_f32 v42, v14, v15
	v_cvt_pk_bf16_f32 v43, v16, v17
	v_lshl_add_u64 v[48:49], s[12:13], 0, v[46:47]
	v_cvt_pk_bf16_f32 v44, v10, v11
	v_cvt_pk_bf16_f32 v45, v12, v13
	v_lshl_add_u64 v[46:47], s[18:19], 0, v[46:47]
	v_pk_mul_f32 v[48:49], v[68:69], v[12:13]
	v_pk_mul_f32 v[42:43], v[70:71], v[14:15]
	v_pk_mul_f32 v[44:45], v[72:73], v[16:17]
	v_cvt_pk_bf16_f32 v42, v42, v43
	v_pk_mul_f32 v[50:51], v[66:67], v[10:11]
	v_cvt_pk_bf16_f32 v43, v44, v45
	v_pk_fma_f32 v[2:3], v[2:3], v[74:75], v[38:39]
	v_cvt_pk_bf16_f32 v44, v50, v51
	v_cvt_pk_bf16_f32 v45, v48, v49
	flat_store_dwordx4 v[46:47], v[42:45] sc1
	v_pk_fma_f32 v[8:9], v[8:9], v[80:81], v[36:37]
	v_pk_fma_f32 v[6:7], v[6:7], v[78:79], v[34:35]
	v_lshl_add_u64 v[42:43], v[128:129], 0, v[120:121]
	v_lshlrev_b64 v[38:39], 1, v[42:43]
	v_pk_fma_f32 v[4:5], v[4:5], v[76:77], v[40:41]
	v_cvt_pk_bf16_f32 v34, v6, v7
	v_cvt_pk_bf16_f32 v35, v8, v9
	v_cvt_pk_bf16_f32 v36, v2, v3
	v_lshl_add_u64 v[40:41], s[12:13], 0, v[38:39]
	v_cvt_pk_bf16_f32 v37, v4, v5
	v_pk_mul_f32 v[42:43], v[66:67], v[2:3]
	v_lshl_add_u64 v[38:39], s[18:19], 0, v[38:39]
	v_pk_mul_f32 v[36:37], v[72:73], v[8:9]
	v_pk_mul_f32 v[34:35], v[70:71], v[6:7]
	v_pk_mul_f32 v[40:41], v[68:69], v[4:5]
	v_cvt_pk_bf16_f32 v34, v34, v35
	v_cvt_pk_bf16_f32 v35, v36, v37
	v_cvt_pk_bf16_f32 v36, v42, v43
	ds_swizzle_b32 v42, v96 offset:swizzle(SWAP,16)
	v_cvt_pk_bf16_f32 v37, v40, v41
	flat_store_dwordx4 v[38:39], v[34:37] sc1
	v_cmp_eq_u32_e32 vcc, 0, v245
	s_waitcnt lgkmcnt(0)
	v_add_f32_e32 v36, v96, v42
	v_mov_b32_e32 v37, v36
	s_nop 1
	v_permlane32_swap_b32_e32 v36, v37
	v_lshl_add_u64 v[34:35], v[178:179], 3, s[20:21]
	s_and_saveexec_b64 s[30:31], vcc
	s_cbranch_execz .LBB0_1075
	v_add_f32_e32 v36, v36, v37
	v_mul_f32_e32 v36, 0x49800000, v36
	v_trunc_f32_e32 v36, v36
	v_mul_f32_e64 v37, |v36|, s78
	v_floor_f32_e32 v37, v37
	v_fma_f32 v38, v37, s74, |v36|
	v_cvt_u32_f32_e32 v38, v38
	v_cvt_u32_f32_e32 v37, v37
	v_ashrrev_i32_e32 v39, 31, v36
	v_xor_b32_e32 v36, v38, v39
	v_xor_b32_e32 v37, v37, v39
	v_sub_co_u32_e64 v36, s[8:9], v36, v39
	s_nop 1
	v_subb_co_u32_e64 v37, s[8:9], v37, v39, s[8:9]
	global_atomic_add_x2 v[34:35], v[36:37], off

.LBB0_1292:
	s_nop 1
	v_lshl_add_u64 v[34:35], s[12:13], 0, v[204:205]
	v_lshl_add_u64 v[186:187], v[34:35], 0, v[104:105]
	v_lshl_add_u64 v[34:35], s[12:13], 0, v[206:207]
	v_lshl_add_u64 v[246:247], v[186:187], 0, s[98:99]
	flat_load_dwordx4 v[182:185], v[246:247]
	v_lshl_add_u64 v[36:37], s[12:13], 0, v[208:209]
	v_lshl_add_u64 v[38:39], s[12:13], 0, v[210:211]
	v_lshl_add_u64 v[176:177], v[34:35], 0, v[104:105]
	v_lshl_add_u64 v[124:125], v[36:37], 0, v[104:105]
	v_lshl_add_u64 v[104:105], v[38:39], 0, v[104:105]
	v_lshl_add_u64 v[246:247], v[176:177], 0, s[98:99]
	flat_load_dwordx4 v[42:45], v[246:247]
	v_lshl_add_u64 v[246:247], v[124:125], 0, s[98:99]
	flat_load_dwordx4 v[38:41], v[246:247]
	v_lshl_add_u64 v[246:247], v[104:105], 0, s[98:99]
	flat_load_dwordx4 v[34:37], v[246:247]
	v_lshl_add_u64 v[178:179], v[212:213], 0, v[102:103]
	s_and_b64 vcc, exec, s[8:9]
	s_waitcnt vmcnt(0) lgkmcnt(0)
	v_lshlrev_b32_e32 v188, 16, v182
	v_and_b32_e32 v189, 0xffff0000, v182
	v_lshlrev_b32_e32 v182, 16, v183
	v_and_b32_e32 v183, 0xffff0000, v183
	v_lshlrev_b32_e32 v190, 16, v184
	v_and_b32_e32 v191, 0xffff0000, v184
	v_lshlrev_b32_e32 v184, 16, v185
	v_and_b32_e32 v185, 0xffff0000, v185
	v_pk_mul_f32 v[182:183], v[182:183], v[234:235]
	v_pk_fma_f32 v[32:33], v[32:33], v[88:89], v[182:183]
	v_pk_mul_f32 v[188:189], v[188:189], v[232:233]
	v_pk_fma_f32 v[30:31], v[30:31], v[86:87], v[188:189]
	v_pk_mul_f32 v[190:191], v[190:191], v[240:241]
	v_pk_fma_f32 v[26:27], v[26:27], v[82:83], v[190:191]
	v_pk_mul_f32 v[184:185], v[184:185], v[242:243]
	v_pk_fma_f32 v[28:29], v[28:29], v[84:85], v[184:185]
	v_cvt_pk_bf16_f32 v182, v30, v31
	v_cvt_pk_bf16_f32 v183, v32, v33
	v_cvt_pk_bf16_f32 v184, v26, v27
	s_nop 0
	v_cvt_pk_bf16_f32 v185, v28, v29
	s_cbranch_vccz .Lxs2_13
	flat_store_dwordx4 v[186:187], v[182:185] sc1
.Lxs2_13:
	s_cbranch_vccnz .LBB0_1294
	s_nop 0
	v_pk_mul_f32 v[184:185], v[76:77], v[32:33]
	v_pk_mul_f32 v[182:183], v[74:75], v[30:31]
	v_pk_mul_f32 v[186:187], v[72:73], v[28:29]
	v_pk_mul_f32 v[188:189], v[70:71], v[26:27]
	v_cvt_pk_bf16_f32 v182, v182, v183
	v_cvt_pk_bf16_f32 v183, v184, v185
	s_nop 0
	v_cvt_pk_bf16_f32 v184, v188, v189
	v_cvt_pk_bf16_f32 v185, v186, v187
	v_lshl_add_u64 v[186:187], v[178:179], 1, s[18:19]
	flat_store_dwordx4 v[186:187], v[182:185] sc1
.LBB0_1294:
	s_and_b64 vcc, exec, s[6:7]
	s_cbranch_vccnz .LBB0_1296
	v_pk_mul_f32 v[184:185], v[68:69], v[32:33]
	v_pk_mul_f32 v[182:183], v[66:67], v[30:31]
	v_lshl_add_u64 v[178:179], v[178:179], 1, s[22:23]
	v_pk_mul_f32 v[186:187], v[80:81], v[28:29]
	v_pk_mul_f32 v[188:189], v[78:79], v[26:27]
	v_cvt_pk_bf16_f32 v182, v182, v183
	v_cvt_pk_bf16_f32 v183, v184, v185
	s_nop 0
	v_cvt_pk_bf16_f32 v184, v188, v189
	v_cvt_pk_bf16_f32 v185, v186, v187
	flat_store_dwordx4 v[178:179], v[182:185] sc1
.LBB0_1296:
	v_lshlrev_b32_e32 v178, 16, v42
	v_and_b32_e32 v179, 0xffff0000, v42
	v_lshlrev_b32_e32 v182, 16, v43
	v_and_b32_e32 v183, 0xffff0000, v43
	v_lshlrev_b32_e32 v184, 16, v44
	v_and_b32_e32 v185, 0xffff0000, v44
	v_lshlrev_b32_e32 v44, 16, v45
	v_and_b32_e32 v45, 0xffff0000, v45
	v_lshl_add_u64 v[42:43], v[214:215], 0, v[102:103]
	v_pk_mul_f32 v[182:183], v[182:183], v[234:235]
	v_pk_fma_f32 v[24:25], v[24:25], v[88:89], v[182:183]
	v_pk_mul_f32 v[178:179], v[178:179], v[232:233]
	v_pk_fma_f32 v[22:23], v[22:23], v[86:87], v[178:179]
	v_pk_mul_f32 v[184:185], v[184:185], v[240:241]
	v_pk_fma_f32 v[18:19], v[18:19], v[82:83], v[184:185]
	v_pk_mul_f32 v[44:45], v[44:45], v[242:243]
	v_pk_fma_f32 v[20:21], v[20:21], v[84:85], v[44:45]
	s_and_b64 vcc, exec, s[8:9]
	v_cvt_pk_bf16_f32 v182, v22, v23
	v_cvt_pk_bf16_f32 v183, v24, v25
	v_cvt_pk_bf16_f32 v184, v18, v19
	v_cvt_pk_bf16_f32 v185, v20, v21
	s_cbranch_vccz .Lxs2_14
	flat_store_dwordx4 v[176:177], v[182:185] sc1
.Lxs2_14:
	s_cbranch_vccnz .LBB0_1298
	v_pk_mul_f32 v[44:45], v[76:77], v[24:25]
	v_pk_mul_f32 v[176:177], v[74:75], v[22:23]
	v_pk_mul_f32 v[178:179], v[70:71], v[18:19]
	v_cvt_pk_bf16_f32 v176, v176, v177
	v_cvt_pk_bf16_f32 v177, v44, v45
	v_lshl_add_u64 v[44:45], v[42:43], 1, s[18:19]
	v_pk_mul_f32 v[182:183], v[72:73], v[20:21]
	v_cvt_pk_bf16_f32 v178, v178, v179
	s_nop 0
	v_cvt_pk_bf16_f32 v179, v182, v183
	flat_store_dwordx4 v[44:45], v[176:179] sc1
.LBB0_1298:
	s_and_b64 vcc, exec, s[6:7]
	s_cbranch_vccnz .LBB0_1300
	v_pk_mul_f32 v[176:177], v[66:67], v[22:23]
	v_pk_mul_f32 v[178:179], v[78:79], v[18:19]
	v_lshl_add_u64 v[42:43], v[42:43], 1, s[22:23]
	v_pk_mul_f32 v[44:45], v[68:69], v[24:25]
	v_pk_mul_f32 v[182:183], v[80:81], v[20:21]
	v_cvt_pk_bf16_f32 v176, v176, v177
	v_cvt_pk_bf16_f32 v177, v44, v45
	v_cvt_pk_bf16_f32 v178, v178, v179
	s_nop 0
	v_cvt_pk_bf16_f32 v179, v182, v183
	flat_store_dwordx4 v[42:43], v[176:179] sc1
.LBB0_1300:
	v_lshlrev_b32_e32 v42, 16, v38
	v_and_b32_e32 v43, 0xffff0000, v38
	v_lshlrev_b32_e32 v44, 16, v39
	v_and_b32_e32 v45, 0xffff0000, v39
	v_lshlrev_b32_e32 v176, 16, v40
	v_and_b32_e32 v177, 0xffff0000, v40
	v_lshlrev_b32_e32 v40, 16, v41
	v_and_b32_e32 v41, 0xffff0000, v41
	v_lshl_add_u64 v[38:39], v[216:217], 0, v[102:103]
	v_pk_mul_f32 v[44:45], v[44:45], v[234:235]
	v_pk_fma_f32 v[16:17], v[16:17], v[88:89], v[44:45]
	v_pk_mul_f32 v[42:43], v[42:43], v[232:233]
	v_pk_fma_f32 v[14:15], v[14:15], v[86:87], v[42:43]
	v_pk_mul_f32 v[176:177], v[176:177], v[240:241]
	v_pk_fma_f32 v[10:11], v[10:11], v[82:83], v[176:177]
	v_pk_mul_f32 v[40:41], v[40:41], v[242:243]
	v_pk_fma_f32 v[12:13], v[12:13], v[84:85], v[40:41]
	s_and_b64 vcc, exec, s[8:9]
	v_cvt_pk_bf16_f32 v40, v14, v15
	v_cvt_pk_bf16_f32 v41, v16, v17
	v_cvt_pk_bf16_f32 v42, v10, v11
	v_cvt_pk_bf16_f32 v43, v12, v13
	s_cbranch_vccz .Lxs2_15
	flat_store_dwordx4 v[124:125], v[40:43] sc1
.Lxs2_15:
	s_cbranch_vccnz .LBB0_1302
	s_nop 0
	v_pk_mul_f32 v[42:43], v[76:77], v[16:17]
	v_pk_mul_f32 v[40:41], v[74:75], v[14:15]
	v_pk_mul_f32 v[44:45], v[72:73], v[12:13]
	v_pk_mul_f32 v[124:125], v[70:71], v[10:11]
	v_cvt_pk_bf16_f32 v40, v40, v41
	v_cvt_pk_bf16_f32 v41, v42, v43
	s_nop 0
	v_cvt_pk_bf16_f32 v42, v124, v125
	v_cvt_pk_bf16_f32 v43, v44, v45
	v_lshl_add_u64 v[44:45], v[38:39], 1, s[18:19]
	flat_store_dwordx4 v[44:45], v[40:43] sc1
.LBB0_1302:
	s_and_b64 vcc, exec, s[6:7]
	s_cbranch_vccnz .LBB0_1304
	v_pk_mul_f32 v[42:43], v[68:69], v[16:17]
	v_pk_mul_f32 v[40:41], v[66:67], v[14:15]
	v_lshl_add_u64 v[38:39], v[38:39], 1, s[22:23]
	v_pk_mul_f32 v[44:45], v[80:81], v[12:13]
	v_pk_mul_f32 v[124:125], v[78:79], v[10:11]
	v_cvt_pk_bf16_f32 v40, v40, v41
	v_cvt_pk_bf16_f32 v41, v42, v43
	s_nop 0
	v_cvt_pk_bf16_f32 v42, v124, v125
	v_cvt_pk_bf16_f32 v43, v44, v45
	flat_store_dwordx4 v[38:39], v[40:43] sc1
.LBB0_1304:
	v_lshlrev_b32_e32 v38, 16, v34
	v_and_b32_e32 v39, 0xffff0000, v34
	v_lshlrev_b32_e32 v40, 16, v35
	v_and_b32_e32 v41, 0xffff0000, v35
	v_lshlrev_b32_e32 v42, 16, v36
	v_and_b32_e32 v43, 0xffff0000, v36
	v_lshlrev_b32_e32 v36, 16, v37
	v_and_b32_e32 v37, 0xffff0000, v37
	v_lshl_add_u64 v[34:35], v[122:123], 0, v[102:103]
	v_pk_mul_f32 v[40:41], v[40:41], v[234:235]
	v_pk_fma_f32 v[8:9], v[8:9], v[88:89], v[40:41]
	v_pk_mul_f32 v[38:39], v[38:39], v[232:233]
	v_pk_fma_f32 v[6:7], v[6:7], v[86:87], v[38:39]
	v_pk_mul_f32 v[42:43], v[42:43], v[240:241]
	v_pk_fma_f32 v[2:3], v[2:3], v[82:83], v[42:43]
	v_pk_mul_f32 v[36:37], v[36:37], v[242:243]
	v_pk_fma_f32 v[4:5], v[4:5], v[84:85], v[36:37]
	s_and_b64 vcc, exec, s[8:9]
	v_cvt_pk_bf16_f32 v36, v6, v7
	v_cvt_pk_bf16_f32 v37, v8, v9
	v_cvt_pk_bf16_f32 v38, v2, v3
	v_cvt_pk_bf16_f32 v39, v4, v5
	s_cbranch_vccz .Lxs2_16
	flat_store_dwordx4 v[104:105], v[36:39] sc1
.Lxs2_16:
	s_cbranch_vccnz .LBB0_1324
	s_nop 0
	v_pk_mul_f32 v[38:39], v[76:77], v[8:9]
	v_pk_mul_f32 v[36:37], v[74:75], v[6:7]
	v_pk_mul_f32 v[40:41], v[72:73], v[4:5]
	v_pk_mul_f32 v[42:43], v[70:71], v[2:3]
	v_cvt_pk_bf16_f32 v36, v36, v37
	v_cvt_pk_bf16_f32 v37, v38, v39
	s_nop 0
	v_cvt_pk_bf16_f32 v38, v42, v43
	v_cvt_pk_bf16_f32 v39, v40, v41
	v_lshl_add_u64 v[40:41], v[34:35], 1, s[18:19]
	flat_store_dwordx4 v[40:41], v[36:39] sc1
	s_and_b64 vcc, exec, s[6:7]
	s_cbranch_vccz .LBB0_1325

.LBB0_1325:
	v_pk_mul_f32 v[38:39], v[68:69], v[8:9]
	v_pk_mul_f32 v[36:37], v[66:67], v[6:7]
	v_lshl_add_u64 v[34:35], v[34:35], 1, s[22:23]
	v_pk_mul_f32 v[40:41], v[80:81], v[4:5]
	v_pk_mul_f32 v[42:43], v[78:79], v[2:3]
	v_cvt_pk_bf16_f32 v36, v36, v37
	v_cvt_pk_bf16_f32 v37, v38, v39
	s_nop 0
	v_cvt_pk_bf16_f32 v38, v42, v43
	v_cvt_pk_bf16_f32 v39, v40, v41
	flat_store_dwordx4 v[34:35], v[36:39] sc1
	s_and_b64 vcc, exec, s[10:11]
	s_cbranch_vccnz .LBB0_1307
